# filter nb loop: per-element fwd/bwd exec-masked blocks collapsed to cvt + ds_write (dead address math removed)
# speedup vs baseline: 1.0277x; 1.0024x over previous
; #define MFMA(a, b, c) __builtin_amdgcn_mfma_f32_32x32x16_bf16((a), (b), (c), 0, 0, 0)
; DI f32x16 zero16() { f32x16 z; for (int i = 0; i < 16; ++i) z[i] = 0.f; return z; }
; DI void filter_tile(const P& p, int l, int tile, char* smem) {
;     ...
;   for (int nb = 0; nb < 8; nb += 2) {
;     u32x4 bw[2][4];
; #pragma unroll
;     for (int u = 0; u < 2; ++u) {
;       const int col = wave * 256 + (nb + u) * 32 + li;
; #pragma unroll
;       for (int ks = 0; ks < 4; ++ks) {
;         const float* wp = w4 + (size_t)(16 * ks + 8 * g) * 2048 + col;
;         const float a0 = wp[0], a1 = wp[2048], a2 = wp[2 * 2048], a3 = wp[3 * 2048];
;         const float a4 = wp[4 * 2048], a5 = wp[5 * 2048], a6 = wp[6 * 2048], a7 = wp[7 * 2048];
;         u32x4 t; t[0] = pack2(a0, a1); t[1] = pack2(a2, a3); t[2] = pack2(a4, a5); t[3] = pack2(a6, a7);
;         bw[u][ks] = t;
;       }
;     }
; #pragma unroll
;     for (int u = 0; u < 2; ++u) {
;       const int col = wave * 256 + (nb + u) * 32 + li;
;       f32x16 acc = zero16();
; #pragma unroll
;       for (int ks = 0; ks < 4; ++ks) acc = MFMA(af[ks], __builtin_bit_cast(bf16x8, bw[u][ks]), acc);
.LBB0_183:
	v_lshrrev_b32_e32 v241, 6, v198
	v_mul_u32_u24_e32 v241, 0x900, v241
	v_add_u32_e32 v241, 0x10000, v241
	v_and_b32_e32 v242, 31, v198
	v_bfe_u32 v243, v198, 5, 1
	v_mul_u32_u24_e32 v222, 0x44, v242
	v_lshl_add_u32 v222, v243, 3, v222
	v_add_u32_e32 v222, v222, v241
	v_mul_u32_u24_e32 v223, 0x44, v243
	v_lshl_add_u32 v223, v242, 1, v223
	v_add_u32_e32 v223, v223, v241
	v_add_u32_e32 v244, s64, v242
	v_sub_u32_e32 v245, 0x2000, v244
	v_add_u32_e32 v244, 0x2000, v244
	v_cndmask_b32_e64 v244, v245, v244, s[6:7]
	v_lshlrev_b32_e32 v244, 1, v244
	v_lshl_add_u32 v240, v243, 15, v244
	v_ashrrev_i32_e32 v77, 31, v76
	v_lshl_add_u64 v[4:5], v[76:77], 2, s[70:71]
	v_lshl_add_u64 v[84:85], v[40:41], 2, v[4:5]
	v_add_co_u32_e32 v86, vcc, 0x2000, v84
	s_waitcnt lgkmcnt(0)
	v_lshl_add_u64 v[0:1], v[4:5], 0, v[78:79]
	v_addc_co_u32_e32 v87, vcc, 0, v85, vcc
	v_add_co_u32_e32 v88, vcc, 0x4000, v84
	global_load_dword v90, v[0:1], off
	s_nop 0
	v_addc_co_u32_e32 v89, vcc, 0, v85, vcc
	v_add_co_u32_e32 v6, vcc, 0x6000, v84
	global_load_dword v32, v[84:85], off
	s_nop 0
	v_addc_co_u32_e32 v7, vcc, 0, v85, vcc
	v_add_co_u32_e32 v8, vcc, 0x8000, v84
	global_load_dword v35, v[6:7], off
	s_nop 0
	v_addc_co_u32_e32 v9, vcc, 0, v85, vcc
	v_add_co_u32_e32 v12, vcc, 0xa000, v84
	global_load_dword v36, v[8:9], off
	s_nop 0
	v_addc_co_u32_e32 v13, vcc, 0, v85, vcc
	v_add_co_u32_e32 v14, vcc, 0xc000, v84
	global_load_dword v37, v[12:13], off
	s_nop 0
	v_addc_co_u32_e32 v15, vcc, 0, v85, vcc
	v_add_co_u32_e32 v10, vcc, 0xe000, v84
	global_load_dword v38, v[14:15], off
	s_nop 0
	v_addc_co_u32_e32 v11, vcc, 0, v85, vcc
	v_add_co_u32_e32 v2, vcc, s65, v0
	global_load_dword v39, v[10:11], off
	s_nop 0
	v_addc_co_u32_e32 v3, vcc, 0, v1, vcc
	global_load_dword v91, v[2:3], off
	v_add_co_u32_e32 v2, vcc, s61, v0
	global_load_dword v33, v[86:87], off
	s_nop 0
	v_addc_co_u32_e32 v3, vcc, 0, v1, vcc
	global_load_dword v92, v[2:3], off
	v_add_co_u32_e32 v2, vcc, s2, v0
	global_load_dword v34, v[88:89], off
	s_nop 0
	v_addc_co_u32_e32 v3, vcc, 0, v1, vcc
	global_load_dword v93, v[2:3], off
	v_add_co_u32_e32 v2, vcc, s1, v0
	s_nop 1
	v_addc_co_u32_e32 v3, vcc, 0, v1, vcc
	global_load_dword v94, v[2:3], off
	v_add_co_u32_e32 v2, vcc, s62, v0
	s_nop 1
	v_addc_co_u32_e32 v3, vcc, 0, v1, vcc
	global_load_dword v95, v[2:3], off
	v_add_co_u32_e32 v2, vcc, s63, v0
	s_nop 1
	v_addc_co_u32_e32 v3, vcc, 0, v1, vcc
	v_add_co_u32_e32 v0, vcc, s33, v0
	global_load_dword v96, v[2:3], off
	s_nop 0
	v_addc_co_u32_e32 v1, vcc, 0, v1, vcc
	global_load_dword v97, v[0:1], off
	v_lshl_add_u64 v[0:1], v[4:5], 0, v[80:81]
	v_add_co_u32_e32 v2, vcc, s65, v0
	global_load_dword v98, v[0:1], off
	s_nop 0
	v_addc_co_u32_e32 v3, vcc, 0, v1, vcc
	global_load_dword v99, v[2:3], off
	v_add_co_u32_e32 v2, vcc, s61, v0
	s_nop 1
	v_addc_co_u32_e32 v3, vcc, 0, v1, vcc
	global_load_dword v100, v[2:3], off
	v_add_co_u32_e32 v2, vcc, s2, v0
	s_nop 1
	v_addc_co_u32_e32 v3, vcc, 0, v1, vcc
	global_load_dword v101, v[2:3], off
	v_add_co_u32_e32 v2, vcc, s1, v0
	s_nop 1
	v_addc_co_u32_e32 v3, vcc, 0, v1, vcc
	global_load_dword v102, v[2:3], off
	v_add_co_u32_e32 v2, vcc, s62, v0
	s_nop 1
	v_addc_co_u32_e32 v3, vcc, 0, v1, vcc
	global_load_dword v103, v[2:3], off
	v_add_co_u32_e32 v2, vcc, s63, v0
	s_nop 1
	v_addc_co_u32_e32 v3, vcc, 0, v1, vcc
	v_add_co_u32_e32 v0, vcc, s33, v0
	global_load_dword v104, v[2:3], off
	s_nop 0
	v_addc_co_u32_e32 v1, vcc, 0, v1, vcc
	global_load_dword v105, v[0:1], off
	s_waitcnt vmcnt(19)
	v_cvt_pk_bf16_f32 v2, v36, v37
	s_waitcnt vmcnt(17)
	v_cvt_pk_bf16_f32 v3, v38, v39
	s_waitcnt vmcnt(16)
	v_cvt_pk_bf16_f32 v36, v90, v91
	s_waitcnt vmcnt(15)
	v_cvt_pk_bf16_f32 v0, v32, v33
	s_waitcnt vmcnt(13)
	v_cvt_pk_bf16_f32 v1, v34, v35
	s_waitcnt vmcnt(12)
	v_cvt_pk_bf16_f32 v37, v92, v93
	s_waitcnt vmcnt(10)
	v_cvt_pk_bf16_f32 v38, v94, v95
	s_waitcnt vmcnt(8)
	v_cvt_pk_bf16_f32 v39, v96, v97
	s_waitcnt vmcnt(6)
	v_cvt_pk_bf16_f32 v32, v98, v99
	v_lshl_add_u64 v[98:99], v[4:5], 0, v[82:83]
	v_add_co_u32_e32 v90, vcc, s65, v98
	global_load_dword v92, v[98:99], off
	s_nop 0
	v_addc_co_u32_e32 v91, vcc, 0, v99, vcc
	global_load_dword v94, v[90:91], off
	v_add_co_u32_e32 v90, vcc, s61, v98
	v_lshl_add_u64 v[4:5], v[4:5], 0, s[58:59]
	s_nop 0
	v_addc_co_u32_e32 v91, vcc, 0, v99, vcc
	global_load_dword v96, v[90:91], off
	v_add_co_u32_e32 v90, vcc, s2, v98
	s_waitcnt vmcnt(7)
	v_cvt_pk_bf16_f32 v33, v100, v101
	v_addc_co_u32_e32 v91, vcc, 0, v99, vcc
	global_load_dword v97, v[90:91], off
	v_add_co_u32_e32 v90, vcc, s1, v98
	s_waitcnt vmcnt(6)
	v_cvt_pk_bf16_f32 v34, v102, v103
	v_addc_co_u32_e32 v91, vcc, 0, v99, vcc
	v_add_co_u32_e32 v100, vcc, s62, v98
	global_load_dword v90, v[90:91], off
	s_nop 0
	v_addc_co_u32_e32 v101, vcc, 0, v99, vcc
	global_load_dword v91, v[100:101], off
	v_add_co_u32_e32 v100, vcc, s63, v98
	s_waitcnt vmcnt(6)
; #define MFMA(a, b, c) __builtin_amdgcn_mfma_f32_32x32x16_bf16((a), (b), (c), 0, 0, 0)
; DI f32x16 zero16() { f32x16 z; for (int i = 0; i < 16; ++i) z[i] = 0.f; return z; }
; DI void filter_tile(const P& p, int l, int tile, char* smem) {
;     ...
;   for (int nb = 0; nb < 8; nb += 2) {
;     u32x4 bw[2][4];
; #pragma unroll
;     for (int u = 0; u < 2; ++u) {
;       const int col = wave * 256 + (nb + u) * 32 + li;
; #pragma unroll
;       for (int ks = 0; ks < 4; ++ks) {
;         const float* wp = w4 + (size_t)(16 * ks + 8 * g) * 2048 + col;
;         const float a0 = wp[0], a1 = wp[2048], a2 = wp[2 * 2048], a3 = wp[3 * 2048];
;         const float a4 = wp[4 * 2048], a5 = wp[5 * 2048], a6 = wp[6 * 2048], a7 = wp[7 * 2048];
;         u32x4 t; t[0] = pack2(a0, a1); t[1] = pack2(a2, a3); t[2] = pack2(a4, a5); t[3] = pack2(a6, a7);
;         bw[u][ks] = t;
;       }
;     }
; #pragma unroll
;     for (int u = 0; u < 2; ++u) {
;       const int col = wave * 256 + (nb + u) * 32 + li;
;       f32x16 acc = zero16();
; #pragma unroll
;       for (int ks = 0; ks < 4; ++ks) acc = MFMA(af[ks], __builtin_bit_cast(bf16x8, bw[u][ks]), acc);
	v_cvt_pk_bf16_f32 v35, v104, v105
	v_addc_co_u32_e32 v101, vcc, 0, v99, vcc
	v_add_co_u32_e32 v98, vcc, s33, v98
	global_load_dword v93, v[100:101], off
	s_nop 0
	v_addc_co_u32_e32 v99, vcc, 0, v99, vcc
	global_load_dword v95, v[98:99], off
	global_load_dword v112, v[84:85], off offset:128
	global_load_dword v113, v[86:87], off offset:128
	global_load_dword v115, v[88:89], off offset:128
	global_load_dword v116, v[6:7], off offset:128
	global_load_dword v117, v[8:9], off offset:128
	global_load_dword v118, v[12:13], off offset:128
	global_load_dword v119, v[14:15], off offset:128
	global_load_dword v120, v[10:11], off offset:128
	v_lshl_add_u64 v[6:7], v[4:5], 0, v[78:79]
	v_add_co_u32_e32 v8, vcc, s65, v6
	global_load_dword v121, v[6:7], off
	s_nop 0
	v_addc_co_u32_e32 v9, vcc, 0, v7, vcc
	global_load_dword v122, v[8:9], off
	v_add_co_u32_e32 v8, vcc, s61, v6
	v_lshl_add_u64 v[84:85], v[4:5], 0, v[82:83]
	s_nop 0
	v_addc_co_u32_e32 v9, vcc, 0, v7, vcc
	global_load_dword v123, v[8:9], off
	v_add_co_u32_e32 v8, vcc, s2, v6
	global_load_dword v137, v[84:85], off
	s_nop 0
	v_addc_co_u32_e32 v9, vcc, 0, v7, vcc
	global_load_dword v124, v[8:9], off
	v_add_co_u32_e32 v8, vcc, s1, v6
	s_nop 1
	v_addc_co_u32_e32 v9, vcc, 0, v7, vcc
	global_load_dword v125, v[8:9], off
	v_add_co_u32_e32 v8, vcc, s62, v6
	s_nop 1
	v_addc_co_u32_e32 v9, vcc, 0, v7, vcc
	global_load_dword v126, v[8:9], off
	v_add_co_u32_e32 v8, vcc, s63, v6
	s_nop 1
	v_addc_co_u32_e32 v9, vcc, 0, v7, vcc
	v_add_co_u32_e32 v6, vcc, s33, v6
	global_load_dword v127, v[8:9], off
	s_nop 0
	v_addc_co_u32_e32 v7, vcc, 0, v7, vcc
	global_load_dword v128, v[6:7], off
	v_lshl_add_u64 v[6:7], v[4:5], 0, v[80:81]
	v_add_co_u32_e32 v8, vcc, s65, v6
	global_load_dword v129, v[6:7], off
	s_nop 0
	v_addc_co_u32_e32 v9, vcc, 0, v7, vcc
	global_load_dword v130, v[8:9], off
	v_add_co_u32_e32 v8, vcc, s61, v6
	s_nop 1
	v_addc_co_u32_e32 v9, vcc, 0, v7, vcc
	global_load_dword v131, v[8:9], off
	v_add_co_u32_e32 v8, vcc, s2, v6
	s_nop 1
	v_addc_co_u32_e32 v9, vcc, 0, v7, vcc
	global_load_dword v132, v[8:9], off
	v_add_co_u32_e32 v8, vcc, s1, v6
	s_nop 1
	v_addc_co_u32_e32 v9, vcc, 0, v7, vcc
	global_load_dword v133, v[8:9], off
	v_add_co_u32_e32 v8, vcc, s62, v6
	s_nop 1
	v_addc_co_u32_e32 v9, vcc, 0, v7, vcc
	global_load_dword v134, v[8:9], off
	v_add_co_u32_e32 v8, vcc, s63, v6
	s_nop 1
	v_addc_co_u32_e32 v9, vcc, 0, v7, vcc
	v_add_co_u32_e32 v6, vcc, s33, v6
	global_load_dword v135, v[8:9], off
	s_nop 0
	v_addc_co_u32_e32 v7, vcc, 0, v7, vcc
	v_add_co_u32_e32 v4, vcc, s65, v84
	global_load_dword v136, v[6:7], off
	s_nop 0
	v_addc_co_u32_e32 v5, vcc, 0, v85, vcc
	global_load_dword v138, v[4:5], off
	v_add_co_u32_e32 v4, vcc, s61, v84
	s_nop 1
	v_addc_co_u32_e32 v5, vcc, 0, v85, vcc
	global_load_dword v139, v[4:5], off
	v_add_co_u32_e32 v4, vcc, s2, v84
	s_nop 1
	v_addc_co_u32_e32 v5, vcc, 0, v85, vcc
	global_load_dword v141, v[4:5], off
	v_add_co_u32_e32 v4, vcc, s1, v84
	s_nop 1
	v_addc_co_u32_e32 v5, vcc, 0, v85, vcc
	v_add_co_u32_e32 v86, vcc, s62, v84
	global_load_dword v140, v[4:5], off
	s_nop 0
	v_addc_co_u32_e32 v87, vcc, 0, v85, vcc
	global_load_dword v142, v[86:87], off
	s_waitcnt lgkmcnt(3)
	v_mfma_f32_32x32x16_bf16 v[0:15], v[16:19], v[0:3], 0
	v_add_co_u32_e32 v86, vcc, s63, v84
	s_nop 1
	v_addc_co_u32_e32 v87, vcc, 0, v85, vcc
	global_load_dword v143, v[86:87], off
	s_waitcnt lgkmcnt(2)
	v_mfma_f32_32x32x16_bf16 v[0:15], v[20:23], v[36:39], v[0:15]
	v_add_co_u32_e32 v36, vcc, s33, v84
	s_nop 1
	v_addc_co_u32_e32 v37, vcc, 0, v85, vcc
	global_load_dword v144, v[36:37], off
	v_and_b32_e32 v37, 0x1df, v76
	s_waitcnt lgkmcnt(1)
	v_mfma_f32_32x32x16_bf16 v[0:15], v[24:27], v[32:35], v[0:15]
	v_cvt_f32_u32_e32 v36, v37
	s_waitcnt vmcnt(38)
	v_cvt_pk_bf16_f32 v32, v92, v94
	s_waitcnt vmcnt(36)
	v_cvt_pk_bf16_f32 v33, v96, v97
	s_waitcnt vmcnt(34)
	v_cvt_pk_bf16_f32 v34, v90, v91
	s_waitcnt vmcnt(32)
	v_cvt_pk_bf16_f32 v35, v93, v95
	v_fmamk_f32 v36, v36, 0xbcc4df2d, v201
	s_waitcnt lgkmcnt(0)
; DI u16 f2bf(float a) { return (u16)(pack2(a, 0.f) & 0xffffu); }
; DI int crow(int reg, int g) { return (reg & 3) + 8 * (reg >> 2) + 4 * g; }
; DI void filter_tile(const P& p, int l, int tile, char* smem) {
;     ...
;       const int j = col >> 9, c = col & 511;
;       const int order = j & 1;
;       const bool fwd = j < 2;
;       const float delta = fabsf(min_decay + (float)c * ((max_decay - min_decay) / 511.0f));
;       u16* tb = p.Tb + (size_t)(order * 512 + c) * 16384;
;       float asum = 0.f;
; #pragma unroll
;       for (int reg = 0; reg < 16; ++reg) {
;         const int m = m0 + crow(reg, g);
;         const float t = (float)m / 8191.0f;
;         const float v = acc[reg] * __expf(-t * delta);
;         if (fwd) { tb[8192 - m] = f2bf(v); asum += fabsf(v); }
;         else if (m >= 1) { tb[8192 + m] = f2bf(v); asum += fabsf(v); }
;       }
	v_mfma_f32_32x32x16_bf16 v[0:15], v[28:31], v[32:35], v[0:15]
	v_mul_f32_e64 v32, v47, |v36|
	v_mul_f32_e32 v32, 0x3fb8aa3b, v32
	v_exp_f32_e32 v32, v32
	v_or_b32_e32 v33, v37, v43
	v_lshlrev_b32_e32 v188, 15, v33
	v_lshl_add_u64 v[34:35], s[44:45], 0, v[188:189]
	s_nop 5
	v_mul_f32_e32 v32, v32, v0
	v_and_b32_e32 v0, 0x7fffffff, v32
	v_cvt_pk_bf16_f32 v241, v32, s0
	ds_write_b16 v222, v241 offset:0
	s_andn2_b64 s[80:81], s[6:7], s[10:11]
	v_cndmask_b32_e64 v0, v0, 0, s[80:81]
	v_mul_f32_e64 v32, v49, |v36|
	v_mul_f32_e32 v32, 0x3fb8aa3b, v32
	v_exp_f32_e32 v32, v32
	s_nop 0
	v_mul_f32_e32 v37, v32, v1
	v_and_b32_e32 v1, 0x7fffffff, v37
	v_lshlrev_b32_e32 v32, 1, v42
	v_cvt_pk_bf16_f32 v241, v37, s0
	ds_write_b16 v222, v241 offset:2
	v_mul_f32_e64 v33, v51, |v36|
	v_mul_f32_e32 v33, 0x3fb8aa3b, v33
	v_exp_f32_e32 v33, v33
	s_nop 0
	v_mul_f32_e32 v37, v33, v2
	v_and_b32_e32 v2, 0x7fffffff, v37
	v_cvt_pk_bf16_f32 v241, v37, s0
	ds_write_b16 v222, v241 offset:4
	v_mul_f32_e64 v33, v53, |v36|
	v_mul_f32_e32 v33, 0x3fb8aa3b, v33
	v_exp_f32_e32 v33, v33
	s_nop 0
	v_mul_f32_e32 v37, v33, v3
	v_and_b32_e32 v3, 0x7fffffff, v37
	v_cvt_pk_bf16_f32 v241, v37, s0
	ds_write_b16 v222, v241 offset:6
	v_mul_f32_e64 v33, v55, |v36|
	v_mul_f32_e32 v33, 0x3fb8aa3b, v33
	v_exp_f32_e32 v33, v33
	s_nop 0
	v_mul_f32_e32 v37, v33, v4
	v_and_b32_e32 v4, 0x7fffffff, v37
	v_cvt_pk_bf16_f32 v241, v37, s0
	ds_write_b16 v222, v241 offset:16
	v_mul_f32_e64 v33, v57, |v36|
	v_mul_f32_e32 v33, 0x3fb8aa3b, v33
	v_exp_f32_e32 v33, v33
	s_nop 0
	v_mul_f32_e32 v37, v33, v5
	v_and_b32_e32 v5, 0x7fffffff, v37
	v_cvt_pk_bf16_f32 v241, v37, s0
	ds_write_b16 v222, v241 offset:18
	v_mul_f32_e64 v33, v59, |v36|
	v_mul_f32_e32 v33, 0x3fb8aa3b, v33
	v_exp_f32_e32 v33, v33
	s_nop 0
	v_mul_f32_e32 v37, v33, v6
	v_and_b32_e32 v6, 0x7fffffff, v37
	v_cvt_pk_bf16_f32 v241, v37, s0
	ds_write_b16 v222, v241 offset:20
	v_mul_f32_e64 v33, v61, |v36|
	v_mul_f32_e32 v33, 0x3fb8aa3b, v33
	v_exp_f32_e32 v33, v33
	s_nop 0
	v_mul_f32_e32 v37, v33, v7
	v_and_b32_e32 v7, 0x7fffffff, v37
	v_cvt_pk_bf16_f32 v241, v37, s0
	ds_write_b16 v222, v241 offset:22
	v_mul_f32_e64 v33, v63, |v36|
	v_mul_f32_e32 v33, 0x3fb8aa3b, v33
	v_exp_f32_e32 v33, v33
	s_nop 0
	v_mul_f32_e32 v37, v33, v8
	v_and_b32_e32 v8, 0x7fffffff, v37
	v_cvt_pk_bf16_f32 v241, v37, s0
	ds_write_b16 v222, v241 offset:32
	v_mul_f32_e64 v33, v65, |v36|
	v_mul_f32_e32 v33, 0x3fb8aa3b, v33
	v_exp_f32_e32 v33, v33
	s_nop 0
	v_mul_f32_e32 v37, v33, v9
	v_and_b32_e32 v9, 0x7fffffff, v37
	v_cvt_pk_bf16_f32 v241, v37, s0
	ds_write_b16 v222, v241 offset:34
	v_mul_f32_e64 v33, v67, |v36|
	v_mul_f32_e32 v33, 0x3fb8aa3b, v33
	v_exp_f32_e32 v33, v33
	s_nop 0
	v_mul_f32_e32 v37, v33, v10
	v_and_b32_e32 v10, 0x7fffffff, v37
	v_cvt_pk_bf16_f32 v241, v37, s0
	ds_write_b16 v222, v241 offset:36
	v_mul_f32_e64 v33, v69, |v36|
	v_mul_f32_e32 v33, 0x3fb8aa3b, v33
	v_exp_f32_e32 v33, v33
	s_nop 0
	v_mul_f32_e32 v37, v33, v11
	v_and_b32_e32 v11, 0x7fffffff, v37
	v_cvt_pk_bf16_f32 v241, v37, s0
	ds_write_b16 v222, v241 offset:38
	v_mul_f32_e64 v33, v71, |v36|
	v_mul_f32_e32 v33, 0x3fb8aa3b, v33
	v_exp_f32_e32 v33, v33
	s_nop 0
	v_mul_f32_e32 v37, v33, v12
	v_and_b32_e32 v12, 0x7fffffff, v37
	v_cvt_pk_bf16_f32 v241, v37, s0
	ds_write_b16 v222, v241 offset:48
	v_mul_f32_e64 v33, v73, |v36|
	v_mul_f32_e32 v33, 0x3fb8aa3b, v33
	v_exp_f32_e32 v33, v33
	s_nop 0
	v_mul_f32_e32 v37, v33, v13
	v_and_b32_e32 v13, 0x7fffffff, v37
	v_cvt_pk_bf16_f32 v241, v37, s0
	ds_write_b16 v222, v241 offset:50
	v_mul_f32_e64 v33, v75, |v36|
	v_mul_f32_e32 v33, 0x3fb8aa3b, v33
	v_exp_f32_e32 v33, v33
	s_nop 0
	v_mul_f32_e32 v37, v33, v14
	v_and_b32_e32 v14, 0x7fffffff, v37
	v_cvt_pk_bf16_f32 v241, v37, s0
	ds_write_b16 v222, v241 offset:52
	v_mul_f32_e64 v33, v114, |v36|
	v_mul_f32_e32 v33, 0x3fb8aa3b, v33
	v_exp_f32_e32 v33, v33
	s_nop 0
	v_mul_f32_e32 v37, v33, v15
	v_and_b32_e32 v15, 0x7fffffff, v37
	v_cvt_pk_bf16_f32 v241, v37, s0
	ds_write_b16 v222, v241 offset:54
	s_and_saveexec_b64 s[78:79], s[74:75]
	s_cbranch_execz .LBB0_249

; #define MFMA(a, b, c) __builtin_amdgcn_mfma_f32_32x32x16_bf16((a), (b), (c), 0, 0, 0)
; DI u16 f2bf(float a) { return (u16)(pack2(a, 0.f) & 0xffffu); }
; DI int crow(int reg, int g) { return (reg & 3) + 8 * (reg >> 2) + 4 * g; }
; DI f32x16 zero16() { f32x16 z; for (int i = 0; i < 16; ++i) z[i] = 0.f; return z; }
; DI void filter_tile(const P& p, int l, int tile, char* smem) {
;     ...
; #pragma unroll
;     for (int u = 0; u < 2; ++u) {
;       const int col = wave * 256 + (nb + u) * 32 + li;
;       f32x16 acc = zero16();
; #pragma unroll
;       for (int ks = 0; ks < 4; ++ks) acc = MFMA(af[ks], __builtin_bit_cast(bf16x8, bw[u][ks]), acc);
;       const int j = col >> 9, c = col & 511;
;       const int order = j & 1;
;       const bool fwd = j < 2;
;       const float delta = fabsf(min_decay + (float)c * ((max_decay - min_decay) / 511.0f));
;       u16* tb = p.Tb + (size_t)(order * 512 + c) * 16384;
;       float asum = 0.f;
; #pragma unroll
;       for (int reg = 0; reg < 16; ++reg) {
;         const int m = m0 + crow(reg, g);
;         const float t = (float)m / 8191.0f;
;         const float v = acc[reg] * __expf(-t * delta);
;         if (fwd) { tb[8192 - m] = f2bf(v); asum += fabsf(v); }
;         else if (m >= 1) { tb[8192 + m] = f2bf(v); asum += fabsf(v); }
;       }
.LBB0_251:
	s_or_b64 exec, exec, s[78:79]
	s_waitcnt vmcnt(30)
	v_cvt_pk_bf16_f32 v0, v112, v113
	s_waitcnt vmcnt(28) lgkmcnt(0)
	v_cvt_pk_bf16_f32 v1, v115, v116
	s_waitcnt vmcnt(26)
	v_cvt_pk_bf16_f32 v2, v117, v118
	s_waitcnt vmcnt(24)
	v_cvt_pk_bf16_f32 v3, v119, v120
	s_waitcnt vmcnt(22)
	v_cvt_pk_bf16_f32 v116, v121, v122
	s_waitcnt vmcnt(19)
	v_cvt_pk_bf16_f32 v117, v123, v124
	v_mfma_f32_32x32x16_bf16 v[0:15], v[16:19], v[0:3], 0
	s_waitcnt vmcnt(17)
	v_cvt_pk_bf16_f32 v118, v125, v126
	s_waitcnt vmcnt(15)
	v_cvt_pk_bf16_f32 v119, v127, v128
	s_waitcnt vmcnt(13)
	v_cvt_pk_bf16_f32 v120, v129, v130
	s_waitcnt vmcnt(11)
	v_cvt_pk_bf16_f32 v121, v131, v132
	s_waitcnt vmcnt(9)
	v_cvt_pk_bf16_f32 v122, v133, v134
	s_waitcnt vmcnt(7)
	v_cvt_pk_bf16_f32 v123, v135, v136
	v_add_u32_e32 v33, 32, v76
	v_mfma_f32_32x32x16_bf16 v[0:15], v[20:23], v[116:119], v[0:15]
	v_and_b32_e32 v33, 0x1ff, v33
	v_cvt_f32_u32_e32 v37, v33
	s_waitcnt vmcnt(6)
	v_cvt_pk_bf16_f32 v116, v137, v138
	s_waitcnt vmcnt(4)
	v_cvt_pk_bf16_f32 v117, v139, v141
	s_waitcnt vmcnt(2)
	v_cvt_pk_bf16_f32 v118, v140, v142
	s_waitcnt vmcnt(0)
	v_cvt_pk_bf16_f32 v119, v143, v144
	v_fmamk_f32 v37, v37, 0xbcc4df2d, v201
	v_mfma_f32_32x32x16_bf16 v[0:15], v[24:27], v[120:123], v[0:15]
	v_mul_f32_e64 v39, v47, |v37|
	v_mul_f32_e32 v39, 0x3fb8aa3b, v39
	v_exp_f32_e32 v39, v39
	v_or_b32_e32 v33, v33, v43
	v_lshlrev_b32_e32 v188, 15, v33
	v_lshl_add_u64 v[112:113], s[44:45], 0, v[188:189]
	v_mfma_f32_32x32x16_bf16 v[0:15], v[28:31], v[116:119], v[0:15]
	s_nop 11
	v_mul_f32_e32 v39, v39, v0
	v_and_b32_e32 v0, 0x7fffffff, v39
	v_cvt_pk_bf16_f32 v241, v39, s0
	ds_write_b16 v222, v241 offset:0
	s_andn2_b64 s[80:81], s[6:7], s[10:11]
	v_cndmask_b32_e64 v0, v0, 0, s[80:81]
	v_mul_f32_e64 v33, v49, |v37|
	v_mul_f32_e32 v33, 0x3fb8aa3b, v33
	v_exp_f32_e32 v33, v33
	s_nop 0
	v_mul_f32_e32 v39, v33, v1
	v_and_b32_e32 v1, 0x7fffffff, v39
	v_cvt_pk_bf16_f32 v241, v39, s0
	ds_write_b16 v222, v241 offset:2
	v_mul_f32_e64 v33, v51, |v37|
	v_mul_f32_e32 v33, 0x3fb8aa3b, v33
	v_exp_f32_e32 v33, v33
	s_nop 0
	v_mul_f32_e32 v39, v33, v2
	v_and_b32_e32 v2, 0x7fffffff, v39
	v_cvt_pk_bf16_f32 v241, v39, s0
	ds_write_b16 v222, v241 offset:4
	v_mul_f32_e64 v33, v53, |v37|
	v_mul_f32_e32 v33, 0x3fb8aa3b, v33
	v_exp_f32_e32 v33, v33
	s_nop 0
	v_mul_f32_e32 v39, v33, v3
	v_and_b32_e32 v3, 0x7fffffff, v39
	v_cvt_pk_bf16_f32 v241, v39, s0
	ds_write_b16 v222, v241 offset:6
	v_mul_f32_e64 v33, v55, |v37|
	v_mul_f32_e32 v33, 0x3fb8aa3b, v33
	v_exp_f32_e32 v33, v33
	s_nop 0
	v_mul_f32_e32 v39, v33, v4
	v_and_b32_e32 v4, 0x7fffffff, v39
	v_cvt_pk_bf16_f32 v241, v39, s0
	ds_write_b16 v222, v241 offset:16
	v_mul_f32_e64 v33, v57, |v37|
	v_mul_f32_e32 v33, 0x3fb8aa3b, v33
	v_exp_f32_e32 v33, v33
	s_nop 0
	v_mul_f32_e32 v39, v33, v5
	v_and_b32_e32 v5, 0x7fffffff, v39
	v_cvt_pk_bf16_f32 v241, v39, s0
	ds_write_b16 v222, v241 offset:18
	v_mul_f32_e64 v33, v59, |v37|
	v_mul_f32_e32 v33, 0x3fb8aa3b, v33
	v_exp_f32_e32 v33, v33
	s_nop 0
	v_mul_f32_e32 v39, v33, v6
	v_and_b32_e32 v6, 0x7fffffff, v39
	v_cvt_pk_bf16_f32 v241, v39, s0
	ds_write_b16 v222, v241 offset:20
	v_mul_f32_e64 v33, v61, |v37|
	v_mul_f32_e32 v33, 0x3fb8aa3b, v33
	v_exp_f32_e32 v33, v33
	s_nop 0
	v_mul_f32_e32 v39, v33, v7
	v_and_b32_e32 v7, 0x7fffffff, v39
	v_cvt_pk_bf16_f32 v241, v39, s0
	ds_write_b16 v222, v241 offset:22
	v_mul_f32_e64 v33, v63, |v37|
	v_mul_f32_e32 v33, 0x3fb8aa3b, v33
	v_exp_f32_e32 v33, v33
	s_nop 0
	v_mul_f32_e32 v39, v33, v8
	v_and_b32_e32 v8, 0x7fffffff, v39
	v_cvt_pk_bf16_f32 v241, v39, s0
	ds_write_b16 v222, v241 offset:32
	v_mul_f32_e64 v33, v65, |v37|
	v_mul_f32_e32 v33, 0x3fb8aa3b, v33
	v_exp_f32_e32 v33, v33
	s_nop 0
	v_mul_f32_e32 v39, v33, v9
	v_and_b32_e32 v9, 0x7fffffff, v39
	v_cvt_pk_bf16_f32 v241, v39, s0
	ds_write_b16 v222, v241 offset:34
	v_mul_f32_e64 v33, v67, |v37|
	v_mul_f32_e32 v33, 0x3fb8aa3b, v33
	v_exp_f32_e32 v33, v33
	s_nop 0
	v_mul_f32_e32 v39, v33, v10
	v_and_b32_e32 v10, 0x7fffffff, v39
	v_cvt_pk_bf16_f32 v241, v39, s0
	ds_write_b16 v222, v241 offset:36
	v_mul_f32_e64 v33, v69, |v37|
	v_mul_f32_e32 v33, 0x3fb8aa3b, v33
	v_exp_f32_e32 v33, v33
	s_nop 0
	v_mul_f32_e32 v39, v33, v11
	v_and_b32_e32 v11, 0x7fffffff, v39
	v_cvt_pk_bf16_f32 v241, v39, s0
	ds_write_b16 v222, v241 offset:38
	v_mul_f32_e64 v33, v71, |v37|
	v_mul_f32_e32 v33, 0x3fb8aa3b, v33
	v_exp_f32_e32 v33, v33
	s_nop 0
	v_mul_f32_e32 v39, v33, v12
	v_and_b32_e32 v12, 0x7fffffff, v39
	v_cvt_pk_bf16_f32 v241, v39, s0
	ds_write_b16 v222, v241 offset:48
	v_mul_f32_e64 v33, v73, |v37|
	v_mul_f32_e32 v33, 0x3fb8aa3b, v33
	v_exp_f32_e32 v33, v33
	s_nop 0
	v_mul_f32_e32 v39, v33, v13
	v_and_b32_e32 v13, 0x7fffffff, v39
	v_cvt_pk_bf16_f32 v241, v39, s0
	ds_write_b16 v222, v241 offset:50
	v_mul_f32_e64 v33, v75, |v37|
	v_mul_f32_e32 v33, 0x3fb8aa3b, v33
	v_exp_f32_e32 v33, v33
	s_nop 0
	v_mul_f32_e32 v39, v33, v14
	v_and_b32_e32 v14, 0x7fffffff, v39
	v_cvt_pk_bf16_f32 v241, v39, s0
	ds_write_b16 v222, v241 offset:52
	v_mul_f32_e64 v33, v114, |v37|
	v_mul_f32_e32 v33, 0x3fb8aa3b, v33
	v_exp_f32_e32 v33, v33
	s_nop 0
	v_mul_f32_e32 v37, v33, v15
	v_and_b32_e32 v15, 0x7fffffff, v37
	v_cvt_pk_bf16_f32 v241, v37, s0
	ds_write_b16 v222, v241 offset:54
	s_and_saveexec_b64 s[78:79], s[74:75]
	s_cbranch_execz .LBB0_317

; DI u16 f2bf(float a) { return (u16)(pack2(a, 0.f) & 0xffffu); }
; DI int crow(int reg, int g) { return (reg & 3) + 8 * (reg >> 2) + 4 * g; }
; DI void filter_tile(const P& p, int l, int tile, char* smem) {
;     ...
;       for (int reg = 0; reg < 16; ++reg) {
;         const int m = m0 + crow(reg, g);
;         const float t = (float)m / 8191.0f;
;         const float v = acc[reg] * __expf(-t * delta);
;         if (fwd) { tb[8192 - m] = f2bf(v); asum += fabsf(v); }
;         else if (m >= 1) { tb[8192 + m] = f2bf(v); asum += fabsf(v); }
;       }
;       if (fwd && tile == 0 && g == 0) tb[0] = 0;
;       asum += __shfl_xor(asum, 32);
;       if (g == 0) p.npart[(size_t)tile * 2048 + col] = asum;
.LBB0_317:
	s_or_b64 exec, exec, s[78:79]
	s_waitcnt lgkmcnt(0)
	ds_read_u16 v224, v223 offset:0
	ds_read_u16 v225, v223 offset:136
	ds_read_u16 v226, v223 offset:272
	ds_read_u16 v227, v223 offset:408
	ds_read_u16 v228, v223 offset:544
	ds_read_u16 v229, v223 offset:680
	ds_read_u16 v230, v223 offset:816
	ds_read_u16 v231, v223 offset:952
	ds_read_u16 v232, v223 offset:1088
	ds_read_u16 v233, v223 offset:1224
	ds_read_u16 v234, v223 offset:1360
	ds_read_u16 v235, v223 offset:1496
	ds_read_u16 v236, v223 offset:1632
	ds_read_u16 v237, v223 offset:1768
	ds_read_u16 v238, v223 offset:1904
	ds_read_u16 v239, v223 offset:2040
	v_readfirstlane_b32 s78, v112
	v_readfirstlane_b32 s79, v113
	v_mov_b32_e32 v246, v240
	v_and_b32_e32 v247, 0x7fff, v240
	v_cmp_eq_u32_e32 vcc, 0x4000, v247
	s_nop 1
	s_and_b64 s[80:81], vcc, s[6:7]
	s_andn2_b64 exec, exec, s[80:81]
	s_waitcnt lgkmcnt(0)
	global_store_short v246, v224, s[78:79]
	v_add_u32_e32 v246, 0x10000, v246
	global_store_short v246, v225, s[78:79]
	v_add_u32_e32 v246, 0x10000, v246
	global_store_short v246, v226, s[78:79]
	v_add_u32_e32 v246, 0x10000, v246
	global_store_short v246, v227, s[78:79]
	v_add_u32_e32 v246, 0x10000, v246
	global_store_short v246, v228, s[78:79]
	v_add_u32_e32 v246, 0x10000, v246
	global_store_short v246, v229, s[78:79]
	v_add_u32_e32 v246, 0x10000, v246
	global_store_short v246, v230, s[78:79]
	v_add_u32_e32 v246, 0x10000, v246
	global_store_short v246, v231, s[78:79]
	v_add_u32_e32 v246, 0x10000, v246
	global_store_short v246, v232, s[78:79]
	v_add_u32_e32 v246, 0x10000, v246
	global_store_short v246, v233, s[78:79]
	v_add_u32_e32 v246, 0x10000, v246
	global_store_short v246, v234, s[78:79]
	v_add_u32_e32 v246, 0x10000, v246
	global_store_short v246, v235, s[78:79]
	v_add_u32_e32 v246, 0x10000, v246
	global_store_short v246, v236, s[78:79]
	v_add_u32_e32 v246, 0x10000, v246
	global_store_short v246, v237, s[78:79]
	v_add_u32_e32 v246, 0x10000, v246
	global_store_short v246, v238, s[78:79]
	v_add_u32_e32 v246, 0x10000, v246
	global_store_short v246, v239, s[78:79]
	s_mov_b64 exec, -1
	v_add_f32_e32 v0, v0, v1
	v_add_f32_e32 v0, v0, v2
	v_add_f32_e32 v0, v0, v3
	v_add_f32_e32 v0, v0, v4
	v_add_f32_e32 v0, v0, v5
	v_add_f32_e32 v0, v0, v6
	v_add_f32_e32 v0, v0, v7
	v_add_f32_e32 v0, v0, v8
	v_add_f32_e32 v0, v0, v9
	v_add_f32_e32 v0, v0, v10
	v_add_f32_e32 v0, v0, v11
	v_add_f32_e32 v0, v0, v12
	v_add_f32_e32 v0, v0, v13
	v_add_f32_e32 v0, v0, v14
	v_add_f32_e32 v0, v0, v15
	ds_bpermute_b32 v1, v45, v0
	s_and_saveexec_b64 s[78:79], s[8:9]
	s_cbranch_execz .LBB0_182
	s_waitcnt lgkmcnt(0)
	v_add_f32_e32 v0, v0, v1
	global_store_dword v[34:35], v0, off offset:128
	s_branch .LBB0_182
.LBB0_323:
	s_mov_b64 s[6:7], 0
